# CONV weight-transpose items: first LDS write waits on its own load only (vmcnt(15) instead of vmcnt(0)) at five sites
# speedup vs baseline: 1.0030x; 1.0016x over previous
; #define LAS __attribute__((address_space(3)))
; template <class RowMap>
; __device__ __forceinline__ void transpose_item(const float* W, int K, int N, int ldw, bf16_t* WT, const RowMap& rm, LAS float* scr, int item, int lane, const float* kscale = nullptr) {
;     const int nblk = N / 64, kb = item / nblk, nb = item % nblk, k0 = 64 * kb, n0 = 64 * nb;
;     f32x4 v[16]; float ksc[16];
; #pragma unroll
;     for (int i = 0; i < 16; ++i) { const int kk = 4 * i + (lane >> 4), c4 = (lane & 15) * 4;
;         v[i] = __builtin_nontemporal_load((const f32x4*)(W + (size_t)(k0 + kk) * ldw + n0 + c4)); ksc[i] = kscale ? kscale[k0 + kk] : 1.0f; }
;     __builtin_amdgcn_sched_barrier(0);
; #pragma unroll
;     for (int i = 0; i < 16; ++i) { const int kk = 4 * i + (lane >> 4), c4 = (lane & 15) * 4; const f32x4 w = kscale ? v[i] * ksc[i] : v[i];
;         scr[kk * 65 + c4] = w[0]; scr[kk * 65 + c4 + 1] = w[1]; scr[kk * 65 + c4 + 2] = w[2]; scr[kk * 65 + c4 + 3] = w[3]; }
;     asm volatile("s_waitcnt lgkmcnt(0)" ::: "memory");
;     const int c = lane & 7;
; #pragma unroll
;     for (int j = 0; j < 8; ++j) { const int n = (lane >> 3) + 8 * j; const LAS float* s = scr + (8 * c) * 65 + n;
;         u32x4 o; o.x = pk2(s[0 * 65], s[1 * 65]); o.y = pk2(s[2 * 65], s[3 * 65]); o.z = pk2(s[4 * 65], s[5 * 65]); o.w = pk2(s[6 * 65], s[7 * 65]);
;         __builtin_nontemporal_store(o, (u32x4*)(WT + (size_t)rm(n0 + n) * K + k0 + 8 * c)); }
;     asm volatile("s_waitcnt lgkmcnt(0)" ::: "memory");
; }
; __global__ void __launch_bounds__(512, 2) mk_fwd(Args args) {
;     ...
;             REP(PH_CONV) for (int it = gw; it < NITEMS; it += NGW) {
;                 int r = it;
;                 if (r < I_IN) { transpose_item(w_in, DM, INW, INW, WB + WE_IN, RowWin{}, scr, r, lane); continue; } r -= I_IN;
;                 if (r < I_UQ) { transpose_item(w_uq, 512, 1536, 1536, WB + WE_UQ, RowUQ{}, scr, r, lane, args.in[I_QN + zz] + (size_t)l * 512); continue; } r -= I_UQ;
;                 if (r < I_UKV) { transpose_item(w_ukv, 512, 2048, 2048, WB + WE_UKV, RowUKV{}, scr, r, lane, args.in[I_KVN + zz] + (size_t)l * 512); continue; } r -= I_UKV;
;                 if (r < 3 * I_BR) { const int n = r / I_BR; transpose_item(w_br + (size_t)n * 1024 * DM, 1024, DM, DM, WB + WE_BR + (size_t)n * DM * 1024, RowId{0}, scr, r - n * I_BR, lane); continue; } r -= 3 * I_BR;
.LBB0_12:
	s_cmpk_gt_i32 s0, 0x181f
	s_mov_b64 s[4:5], -1
	s_cbranch_scc0 .LBB0_98
	s_cmpk_gt_u32 s0, 0x18df
	s_cbranch_scc0 .LBB0_63
	s_cmpk_gt_u32 s0, 0x19df
	s_cbranch_scc0 .LBB0_28
	s_cmpk_gt_u32 s0, 0x1fdf
	s_cbranch_scc0 .LBB0_25
	s_cmpk_gt_u32 s0, 0x23df
	s_cbranch_scc0 .LBB0_22
	s_cmpk_gt_u32 s0, 0x39df
	s_cbranch_scc0 .LBB0_19
	s_and_b32 s5, s28, 0x1ffc0
	s_and_b32 s4, s26, 0x7c0
	v_or_b32_e32 v4, s5, v67
	s_lshl_b32 s30, s4, 2
	v_lshl_add_u64 v[2:3], v[72:73], 0, s[30:31]
	v_lshlrev_b32_e32 v178, 13, v4
	v_lshl_add_u64 v[58:59], v[2:3], 0, v[178:179]
	v_add_co_u32_e32 v6, vcc, 0x8000, v58
	s_nop 1
	v_addc_co_u32_e32 v7, vcc, 0, v59, vcc
	v_add_co_u32_e32 v10, vcc, 0x10000, v58
	global_load_dwordx4 v[2:5], v[58:59], off nt
	s_nop 0
	global_load_dwordx4 v[6:9], v[6:7], off nt
	v_addc_co_u32_e32 v11, vcc, 0, v59, vcc
	v_add_co_u32_e32 v14, vcc, 0x18000, v58
	s_nop 1
	v_addc_co_u32_e32 v15, vcc, 0, v59, vcc
	v_add_co_u32_e32 v18, vcc, 0x20000, v58
	global_load_dwordx4 v[10:13], v[10:11], off nt
	s_nop 0
	global_load_dwordx4 v[14:17], v[14:15], off nt
	v_addc_co_u32_e32 v19, vcc, 0, v59, vcc
	v_add_co_u32_e32 v22, vcc, 0x28000, v58
	s_nop 1
	v_addc_co_u32_e32 v23, vcc, 0, v59, vcc
	v_add_co_u32_e32 v26, vcc, 0x30000, v58
	global_load_dwordx4 v[18:21], v[18:19], off nt
	s_nop 0
	global_load_dwordx4 v[22:25], v[22:23], off nt
	v_addc_co_u32_e32 v27, vcc, 0, v59, vcc
	v_add_co_u32_e32 v30, vcc, 0x38000, v58
	s_nop 1
	v_addc_co_u32_e32 v31, vcc, 0, v59, vcc
	v_add_co_u32_e32 v34, vcc, 0x40000, v58
	global_load_dwordx4 v[26:29], v[26:27], off nt
	s_nop 0
	global_load_dwordx4 v[30:33], v[30:31], off nt
	v_addc_co_u32_e32 v35, vcc, 0, v59, vcc
	v_add_co_u32_e32 v38, vcc, 0x48000, v58
	s_nop 1
	v_addc_co_u32_e32 v39, vcc, 0, v59, vcc
	v_add_co_u32_e32 v42, vcc, 0x50000, v58
	global_load_dwordx4 v[34:37], v[34:35], off nt
	s_nop 0
	global_load_dwordx4 v[38:41], v[38:39], off nt
	v_addc_co_u32_e32 v43, vcc, 0, v59, vcc
	v_add_co_u32_e32 v46, vcc, 0x58000, v58
	s_nop 1
	v_addc_co_u32_e32 v47, vcc, 0, v59, vcc
	v_add_co_u32_e32 v50, vcc, 0x60000, v58
	global_load_dwordx4 v[42:45], v[42:43], off nt
	s_nop 0
	global_load_dwordx4 v[46:49], v[46:47], off nt
	v_addc_co_u32_e32 v51, vcc, 0, v59, vcc
	v_add_co_u32_e32 v54, vcc, 0x68000, v58
	s_nop 1
	v_addc_co_u32_e32 v55, vcc, 0, v59, vcc
	v_add_co_u32_e32 v60, vcc, 0x70000, v58
	global_load_dwordx4 v[50:53], v[50:51], off nt
	s_nop 0
	global_load_dwordx4 v[54:57], v[54:55], off nt
	v_addc_co_u32_e32 v61, vcc, 0, v59, vcc
	v_add_co_u32_e32 v62, vcc, 0x78000, v58
	s_nop 1
	v_addc_co_u32_e32 v63, vcc, 0, v59, vcc
	global_load_dwordx4 v[58:61], v[60:61], off nt
	s_nop 0
	global_load_dwordx4 v[62:65], v[62:63], off nt
	s_waitcnt vmcnt(15)
	ds_write2_b32 v69, v2, v3 offset1:1
	ds_write2_b32 v69, v4, v5 offset0:2 offset1:3
	v_add_u32_e32 v2, 0x410, v69
	s_waitcnt vmcnt(14)
	ds_write2_b32 v2, v6, v7 offset1:1
	v_add_u32_e32 v2, 0x418, v69
	ds_write2_b32 v2, v8, v9 offset1:1
	v_add_u32_e32 v2, 0x820, v69
	s_waitcnt vmcnt(13)
	ds_write2_b32 v2, v10, v11 offset1:1
	v_add_u32_e32 v2, 0x828, v69
	ds_write2_b32 v2, v12, v13 offset1:1
	v_add_u32_e32 v2, 0xc30, v69
	s_waitcnt vmcnt(12)
	ds_write2_b32 v2, v14, v15 offset1:1
	v_add_u32_e32 v2, 0xc38, v69
	ds_write2_b32 v2, v16, v17 offset1:1
	v_add_u32_e32 v2, 0x1040, v69
	s_waitcnt vmcnt(11)
	ds_write2_b32 v2, v18, v19 offset1:1
	v_add_u32_e32 v2, 0x1048, v69
	ds_write2_b32 v2, v20, v21 offset1:1
	v_add_u32_e32 v2, 0x1450, v69
	s_waitcnt vmcnt(10)
	ds_write2_b32 v2, v22, v23 offset1:1
	v_add_u32_e32 v2, 0x1458, v69
	ds_write2_b32 v2, v24, v25 offset1:1
	v_add_u32_e32 v2, 0x1860, v69
	s_waitcnt vmcnt(9)
	ds_write2_b32 v2, v26, v27 offset1:1
	v_add_u32_e32 v2, 0x1868, v69
	ds_write2_b32 v2, v28, v29 offset1:1
	v_add_u32_e32 v2, 0x1c70, v69
	s_waitcnt vmcnt(8)
	ds_write2_b32 v2, v30, v31 offset1:1
	v_add_u32_e32 v2, 0x1c78, v69
	ds_write2_b32 v2, v32, v33 offset1:1
	v_add_u32_e32 v2, 0x2080, v69
	s_waitcnt vmcnt(7)
	ds_write2_b32 v2, v34, v35 offset1:1
	v_add_u32_e32 v2, 0x2088, v69
	ds_write2_b32 v2, v36, v37 offset1:1
	v_add_u32_e32 v2, 0x2490, v69
	s_waitcnt vmcnt(6)
	ds_write2_b32 v2, v38, v39 offset1:1
	v_add_u32_e32 v2, 0x2498, v69
	ds_write2_b32 v2, v40, v41 offset1:1
	v_add_u32_e32 v2, 0x28a0, v69
	s_waitcnt vmcnt(5)
	ds_write2_b32 v2, v42, v43 offset1:1
	v_add_u32_e32 v2, 0x28a8, v69
	ds_write2_b32 v2, v44, v45 offset1:1
	v_add_u32_e32 v2, 0x2cb0, v69
	s_waitcnt vmcnt(4)
	ds_write2_b32 v2, v46, v47 offset1:1
	v_add_u32_e32 v2, 0x2cb8, v69
	ds_write2_b32 v2, v48, v49 offset1:1
	v_add_u32_e32 v2, 0x30c0, v69
	s_waitcnt vmcnt(3)
	ds_write2_b32 v2, v50, v51 offset1:1
	v_add_u32_e32 v2, 0x30c8, v69
	ds_write2_b32 v2, v52, v53 offset1:1
	v_add_u32_e32 v2, 0x34d0, v69
	s_waitcnt vmcnt(2)
	ds_write2_b32 v2, v54, v55 offset1:1
	v_add_u32_e32 v2, 0x34d8, v69
	ds_write2_b32 v2, v56, v57 offset1:1
	v_add_u32_e32 v2, 0x38e0, v69
	s_waitcnt vmcnt(1)
	ds_write2_b32 v2, v58, v59 offset1:1
	v_add_u32_e32 v2, 0x38e8, v69
	ds_write2_b32 v2, v60, v61 offset1:1
	v_add_u32_e32 v2, 0x3cf0, v69
	s_waitcnt vmcnt(0)
	ds_write2_b32 v2, v62, v63 offset1:1
	v_add_u32_e32 v2, 0x3cf8, v69
	ds_write2_b32 v2, v64, v65 offset1:1
	s_waitcnt lgkmcnt(0)
	ds_read2_b32 v[6:7], v101 offset0:65 offset1:73
	ds_read2_b32 v[8:9], v101 offset1:8
	ds_read2_b32 v[10:11], v101 offset0:130 offset1:138
	ds_read2_b32 v[12:13], v101 offset0:195 offset1:203
	v_add_u32_e32 v26, 0x400, v101
	ds_read2_b32 v[14:15], v26 offset0:4 offset1:12
	ds_read2_b32 v[16:17], v26 offset0:69 offset1:77
	ds_read2_b32 v[18:19], v26 offset0:134 offset1:142
	ds_read2_b32 v[20:21], v26 offset0:199 offset1:207
	s_waitcnt lgkmcnt(6)
; #define LAS __attribute__((address_space(3)))
; __device__ __forceinline__ unsigned pk2(float lo, float hi) { const f32x2_g v = {lo, hi}; return __builtin_bit_cast(unsigned, __builtin_convertvector(v, bf16x2_g)); }
; template <class RowMap>
; __device__ __forceinline__ void transpose_item(const float* W, int K, int N, int ldw, bf16_t* WT, const RowMap& rm, LAS float* scr, int item, int lane, const float* kscale = nullptr) {
;     ...
;     asm volatile("s_waitcnt lgkmcnt(0)" ::: "memory");
;     const int c = lane & 7;
; #pragma unroll
;     for (int j = 0; j < 8; ++j) { const int n = (lane >> 3) + 8 * j; const LAS float* s = scr + (8 * c) * 65 + n;
;         u32x4 o; o.x = pk2(s[0 * 65], s[1 * 65]); o.y = pk2(s[2 * 65], s[3 * 65]); o.z = pk2(s[4 * 65], s[5 * 65]); o.w = pk2(s[6 * 65], s[7 * 65]);
;         __builtin_nontemporal_store(o, (u32x4*)(WT + (size_t)rm(n0 + n) * K + k0 + 8 * c)); }
;     asm volatile("s_waitcnt lgkmcnt(0)" ::: "memory");
; }
	v_cvt_pk_bf16_f32 v2, v8, v6
	v_or_b32_e32 v6, s4, v71
	s_lshl_b32 s30, s5, 1
	v_mul_u32_u24_e32 v6, 0x1600, v6
	v_lshl_add_u64 v[22:23], v[74:75], 0, s[30:31]
	v_lshlrev_b32_e32 v178, 1, v6
	s_waitcnt lgkmcnt(4)
	v_cvt_pk_bf16_f32 v3, v10, v12
	s_waitcnt lgkmcnt(2)
	v_cvt_pk_bf16_f32 v4, v14, v16
	s_waitcnt lgkmcnt(0)
	v_cvt_pk_bf16_f32 v5, v18, v20
	v_lshl_add_u64 v[24:25], v[22:23], 0, v[178:179]
	v_or_b32_e32 v6, s4, v103
	global_store_dwordx4 v[24:25], v[2:5], off nt
	v_mul_u32_u24_e32 v6, 0x1600, v6
	v_lshlrev_b32_e32 v178, 1, v6
	v_cvt_pk_bf16_f32 v2, v9, v7
	v_cvt_pk_bf16_f32 v3, v11, v13
	v_cvt_pk_bf16_f32 v4, v15, v17
	v_cvt_pk_bf16_f32 v5, v19, v21
	ds_read2_b32 v[8:9], v101 offset0:16 offset1:24
	ds_read2_b32 v[10:11], v101 offset0:81 offset1:89
	ds_read2_b32 v[12:13], v101 offset0:146 offset1:154
	ds_read2_b32 v[14:15], v101 offset0:211 offset1:219
	ds_read2_b32 v[16:17], v26 offset0:20 offset1:28
	ds_read2_b32 v[18:19], v26 offset0:85 offset1:93
	ds_read2_b32 v[20:21], v26 offset0:150 offset1:158
	ds_read2_b32 v[24:25], v26 offset0:215 offset1:223
	v_lshl_add_u64 v[6:7], v[22:23], 0, v[178:179]
	global_store_dwordx4 v[6:7], v[2:5], off nt
	v_or_b32_e32 v6, s4, v105
	v_mul_u32_u24_e32 v6, 0x1600, v6
	v_lshlrev_b32_e32 v178, 1, v6
	s_waitcnt lgkmcnt(6)
	v_cvt_pk_bf16_f32 v2, v8, v10
	s_waitcnt lgkmcnt(4)
	v_cvt_pk_bf16_f32 v3, v12, v14
	s_waitcnt lgkmcnt(2)
	v_cvt_pk_bf16_f32 v4, v16, v18
	s_waitcnt lgkmcnt(0)
	v_cvt_pk_bf16_f32 v5, v20, v24
	v_lshl_add_u64 v[6:7], v[22:23], 0, v[178:179]
	global_store_dwordx4 v[6:7], v[2:5], off nt
	v_or_b32_e32 v6, s4, v107
	v_mul_u32_u24_e32 v6, 0x1600, v6
	v_cvt_pk_bf16_f32 v2, v9, v11
	v_cvt_pk_bf16_f32 v3, v13, v15
	v_cvt_pk_bf16_f32 v4, v17, v19
	v_cvt_pk_bf16_f32 v5, v21, v25
	v_lshlrev_b32_e32 v178, 1, v6
	ds_read2_b32 v[8:9], v101 offset0:32 offset1:40
	ds_read2_b32 v[10:11], v101 offset0:97 offset1:105
	ds_read2_b32 v[12:13], v101 offset0:162 offset1:170
	ds_read2_b32 v[14:15], v101 offset0:227 offset1:235
	ds_read2_b32 v[16:17], v26 offset0:36 offset1:44
	ds_read2_b32 v[18:19], v26 offset0:101 offset1:109
	ds_read2_b32 v[20:21], v26 offset0:166 offset1:174
	ds_read2_b32 v[24:25], v26 offset0:231 offset1:239
	v_lshl_add_u64 v[6:7], v[22:23], 0, v[178:179]
	global_store_dwordx4 v[6:7], v[2:5], off nt
	v_or_b32_e32 v6, s4, v109
	v_mul_u32_u24_e32 v6, 0x1600, v6
	v_lshlrev_b32_e32 v178, 1, v6
	s_waitcnt lgkmcnt(6)
	v_cvt_pk_bf16_f32 v2, v8, v10
	s_waitcnt lgkmcnt(4)
	v_cvt_pk_bf16_f32 v3, v12, v14
	s_waitcnt lgkmcnt(2)
	v_cvt_pk_bf16_f32 v4, v16, v18
	s_waitcnt lgkmcnt(0)
	v_cvt_pk_bf16_f32 v5, v20, v24
	v_lshl_add_u64 v[6:7], v[22:23], 0, v[178:179]
	global_store_dwordx4 v[6:7], v[2:5], off nt
	v_or_b32_e32 v6, s4, v111
	v_mul_u32_u24_e32 v6, 0x1600, v6
	v_cvt_pk_bf16_f32 v2, v9, v11
	v_cvt_pk_bf16_f32 v3, v13, v15
	v_cvt_pk_bf16_f32 v4, v17, v19
	v_cvt_pk_bf16_f32 v5, v21, v25
	v_lshlrev_b32_e32 v178, 1, v6
	ds_read2_b32 v[8:9], v101 offset0:48 offset1:56
	ds_read2_b32 v[10:11], v101 offset0:113 offset1:121
	ds_read2_b32 v[12:13], v101 offset0:178 offset1:186
	ds_read2_b32 v[14:15], v101 offset0:243 offset1:251
	ds_read2_b32 v[16:17], v26 offset0:52 offset1:60
	ds_read2_b32 v[18:19], v26 offset0:117 offset1:125
	ds_read2_b32 v[20:21], v26 offset0:182 offset1:190
	ds_read2_b32 v[24:25], v26 offset0:247 offset1:255
	v_lshl_add_u64 v[6:7], v[22:23], 0, v[178:179]
	global_store_dwordx4 v[6:7], v[2:5], off nt
	v_or_b32_e32 v6, s4, v113
	v_mul_u32_u24_e32 v6, 0x1600, v6
	v_lshlrev_b32_e32 v178, 1, v6
	s_waitcnt lgkmcnt(6)
	v_cvt_pk_bf16_f32 v2, v8, v10
	s_waitcnt lgkmcnt(4)
	v_cvt_pk_bf16_f32 v3, v12, v14
	s_waitcnt lgkmcnt(2)
	v_cvt_pk_bf16_f32 v4, v16, v18
	s_waitcnt lgkmcnt(0)
	v_cvt_pk_bf16_f32 v5, v20, v24
	v_lshl_add_u64 v[6:7], v[22:23], 0, v[178:179]
	global_store_dwordx4 v[6:7], v[2:5], off nt
	v_or_b32_e32 v6, s4, v115
	v_mul_u32_u24_e32 v6, 0x1600, v6
	v_lshlrev_b32_e32 v178, 1, v6
	v_cvt_pk_bf16_f32 v2, v9, v11
	v_cvt_pk_bf16_f32 v3, v13, v15
	v_cvt_pk_bf16_f32 v4, v17, v19
	v_cvt_pk_bf16_f32 v5, v21, v25
	v_lshl_add_u64 v[6:7], v[22:23], 0, v[178:179]
	global_store_dwordx4 v[6:7], v[2:5], off nt
	s_waitcnt lgkmcnt(0)
	s_mov_b64 s[4:5], 0
.LBB0_19:
	s_andn2_b64 vcc, exec, s[4:5]
	s_cbranch_vccnz .LBB0_21
; #define LAS __attribute__((address_space(3)))
; __device__ __forceinline__ unsigned pk2(float lo, float hi) { const f32x2_g v = {lo, hi}; return __builtin_bit_cast(unsigned, __builtin_convertvector(v, bf16x2_g)); }
; template <class RowMap>
; __device__ __forceinline__ void transpose_item(const float* W, int K, int N, int ldw, bf16_t* WT, const RowMap& rm, LAS float* scr, int item, int lane, const float* kscale = nullptr) {
;     const int nblk = N / 64, kb = item / nblk, nb = item % nblk, k0 = 64 * kb, n0 = 64 * nb;
;     f32x4 v[16]; float ksc[16];
; #pragma unroll
;     for (int i = 0; i < 16; ++i) { const int kk = 4 * i + (lane >> 4), c4 = (lane & 15) * 4;
;         v[i] = __builtin_nontemporal_load((const f32x4*)(W + (size_t)(k0 + kk) * ldw + n0 + c4)); ksc[i] = kscale ? kscale[k0 + kk] : 1.0f; }
;     __builtin_amdgcn_sched_barrier(0);
; #pragma unroll
;     for (int i = 0; i < 16; ++i) { const int kk = 4 * i + (lane >> 4), c4 = (lane & 15) * 4; const f32x4 w = kscale ? v[i] * ksc[i] : v[i];
;         scr[kk * 65 + c4] = w[0]; scr[kk * 65 + c4 + 1] = w[1]; scr[kk * 65 + c4 + 2] = w[2]; scr[kk * 65 + c4 + 3] = w[3]; }
;     asm volatile("s_waitcnt lgkmcnt(0)" ::: "memory");
;     const int c = lane & 7;
; #pragma unroll
;     for (int j = 0; j < 8; ++j) { const int n = (lane >> 3) + 8 * j; const LAS float* s = scr + (8 * c) * 65 + n;
;         u32x4 o; o.x = pk2(s[0 * 65], s[1 * 65]); o.y = pk2(s[2 * 65], s[3 * 65]); o.z = pk2(s[4 * 65], s[5 * 65]); o.w = pk2(s[6 * 65], s[7 * 65]);
;         __builtin_nontemporal_store(o, (u32x4*)(WT + (size_t)rm(n0 + n) * K + k0 + 8 * c)); }
;     asm volatile("s_waitcnt lgkmcnt(0)" ::: "memory");
; }
; __global__ void __launch_bounds__(512, 2) mk_fwd(Args args) {
;     ...
;                 if (r < I_GU) { transpose_item(w_gu, DM, 2 * FF, 2 * FF, WB + WE_GU, RowGU{}, scr, r, lane); continue; } r -= I_GU;
	s_add_i32 s4, s0, 0xdc20
	s_and_b32 s5, s4, 0xffff
	s_mul_i32 s5, s5, 0xba2f
	s_lshr_b32 s6, s5, 23
	s_mul_i32 s5, s6, 0xb0
	s_sub_i32 s5, s4, s5
	s_lshl_b32 s4, s5, 6
	v_lshl_or_b32 v4, s6, 6, v67
	s_and_b32 s4, s4, 0xffc0
	s_lshl_b32 s30, s4, 2
	v_mul_u32_u24_e32 v4, 0x2c00, v4
	v_lshl_add_u64 v[2:3], v[76:77], 0, s[30:31]
	v_lshlrev_b32_e32 v178, 2, v4
	v_lshl_add_u64 v[58:59], v[2:3], 0, v[178:179]
	s_mov_b32 s7, 0x2c000
	v_add_co_u32_e32 v6, vcc, s7, v58
	s_mov_b32 s7, 0x58000
	s_nop 0
	v_addc_co_u32_e32 v7, vcc, 0, v59, vcc
	v_add_co_u32_e32 v10, vcc, s7, v58
	s_mov_b32 s7, 0x84000
	s_nop 0
	v_addc_co_u32_e32 v11, vcc, 0, v59, vcc
	v_add_co_u32_e32 v14, vcc, s7, v58
	s_mov_b32 s7, 0xb0000
	s_nop 0
	v_addc_co_u32_e32 v15, vcc, 0, v59, vcc
	v_add_co_u32_e32 v18, vcc, s7, v58
	s_mov_b32 s7, 0xdc000
	s_nop 0
	v_addc_co_u32_e32 v19, vcc, 0, v59, vcc
	v_add_co_u32_e32 v22, vcc, s7, v58
	s_mov_b32 s7, 0x108000
	s_nop 0
	v_addc_co_u32_e32 v23, vcc, 0, v59, vcc
	v_add_co_u32_e32 v26, vcc, s7, v58
	s_mov_b32 s7, 0x134000
	s_nop 0
	v_addc_co_u32_e32 v27, vcc, 0, v59, vcc
	v_add_co_u32_e32 v30, vcc, s7, v58
	s_mov_b32 s7, 0x160000
	s_nop 0
	v_addc_co_u32_e32 v31, vcc, 0, v59, vcc
	v_add_co_u32_e32 v34, vcc, s7, v58
	s_mov_b32 s7, 0x18c000
	s_nop 0
	v_addc_co_u32_e32 v35, vcc, 0, v59, vcc
	v_add_co_u32_e32 v38, vcc, s7, v58
	s_mov_b32 s7, 0x1b8000
	s_nop 0
	v_addc_co_u32_e32 v39, vcc, 0, v59, vcc
	v_add_co_u32_e32 v42, vcc, s7, v58
	s_mov_b32 s7, 0x1e4000
	s_nop 0
	v_addc_co_u32_e32 v43, vcc, 0, v59, vcc
	v_add_co_u32_e32 v46, vcc, s7, v58
	s_mov_b32 s7, 0x210000
	s_nop 0
	v_addc_co_u32_e32 v47, vcc, 0, v59, vcc
	v_add_co_u32_e32 v50, vcc, s7, v58
	s_mov_b32 s7, 0x23c000
	s_nop 0
	v_addc_co_u32_e32 v51, vcc, 0, v59, vcc
	v_add_co_u32_e32 v54, vcc, s7, v58
	s_mov_b32 s7, 0x268000
	s_nop 0
	v_addc_co_u32_e32 v55, vcc, 0, v59, vcc
	v_add_co_u32_e32 v60, vcc, s7, v58
	s_mov_b32 s7, 0x294000
	s_nop 0
	v_addc_co_u32_e32 v61, vcc, 0, v59, vcc
	v_add_co_u32_e32 v62, vcc, s7, v58
	global_load_dwordx4 v[2:5], v[58:59], off nt
	s_nop 0
	global_load_dwordx4 v[6:9], v[6:7], off nt
	v_addc_co_u32_e32 v63, vcc, 0, v59, vcc
	global_load_dwordx4 v[10:13], v[10:11], off nt
	s_nop 0
	global_load_dwordx4 v[14:17], v[14:15], off nt
	s_nop 0
	global_load_dwordx4 v[18:21], v[18:19], off nt
	s_nop 0
	global_load_dwordx4 v[22:25], v[22:23], off nt
	s_nop 0
	global_load_dwordx4 v[26:29], v[26:27], off nt
	s_nop 0
	global_load_dwordx4 v[30:33], v[30:31], off nt
	s_nop 0
	global_load_dwordx4 v[34:37], v[34:35], off nt
	s_nop 0
	global_load_dwordx4 v[38:41], v[38:39], off nt
	s_nop 0
	global_load_dwordx4 v[42:45], v[42:43], off nt
	s_nop 0
	global_load_dwordx4 v[46:49], v[46:47], off nt
	s_nop 0
	global_load_dwordx4 v[50:53], v[50:51], off nt
	s_nop 0
	global_load_dwordx4 v[54:57], v[54:55], off nt
	s_nop 0
	global_load_dwordx4 v[58:61], v[60:61], off nt
	s_nop 0
	global_load_dwordx4 v[62:65], v[62:63], off nt
	s_waitcnt vmcnt(15)
	ds_write2_b32 v69, v2, v3 offset1:1
	ds_write2_b32 v69, v4, v5 offset0:2 offset1:3
	v_add_u32_e32 v2, 0x410, v69
	s_waitcnt vmcnt(14)
	ds_write2_b32 v2, v6, v7 offset1:1
	v_add_u32_e32 v2, 0x418, v69
	ds_write2_b32 v2, v8, v9 offset1:1
	v_add_u32_e32 v2, 0x820, v69
	s_waitcnt vmcnt(13)
	ds_write2_b32 v2, v10, v11 offset1:1
	v_add_u32_e32 v2, 0x828, v69
	ds_write2_b32 v2, v12, v13 offset1:1
	v_add_u32_e32 v2, 0xc30, v69
	s_waitcnt vmcnt(12)
	ds_write2_b32 v2, v14, v15 offset1:1
	v_add_u32_e32 v2, 0xc38, v69
	ds_write2_b32 v2, v16, v17 offset1:1
	v_add_u32_e32 v2, 0x1040, v69
	s_waitcnt vmcnt(11)
	ds_write2_b32 v2, v18, v19 offset1:1
	v_add_u32_e32 v2, 0x1048, v69
	ds_write2_b32 v2, v20, v21 offset1:1
	v_add_u32_e32 v2, 0x1450, v69
	s_waitcnt vmcnt(10)
	ds_write2_b32 v2, v22, v23 offset1:1
	v_add_u32_e32 v2, 0x1458, v69
	ds_write2_b32 v2, v24, v25 offset1:1
	v_add_u32_e32 v2, 0x1860, v69
	s_waitcnt vmcnt(9)
	ds_write2_b32 v2, v26, v27 offset1:1
	v_add_u32_e32 v2, 0x1868, v69
	ds_write2_b32 v2, v28, v29 offset1:1
	v_add_u32_e32 v2, 0x1c70, v69
	s_waitcnt vmcnt(8)
	ds_write2_b32 v2, v30, v31 offset1:1
	v_add_u32_e32 v2, 0x1c78, v69
	ds_write2_b32 v2, v32, v33 offset1:1
	v_add_u32_e32 v2, 0x2080, v69
	s_waitcnt vmcnt(7)
	ds_write2_b32 v2, v34, v35 offset1:1
	v_add_u32_e32 v2, 0x2088, v69
	ds_write2_b32 v2, v36, v37 offset1:1
	v_add_u32_e32 v2, 0x2490, v69
	s_waitcnt vmcnt(6)
	ds_write2_b32 v2, v38, v39 offset1:1
	v_add_u32_e32 v2, 0x2498, v69
	ds_write2_b32 v2, v40, v41 offset1:1
	v_add_u32_e32 v2, 0x28a0, v69
	s_waitcnt vmcnt(5)
	ds_write2_b32 v2, v42, v43 offset1:1
	v_add_u32_e32 v2, 0x28a8, v69
	ds_write2_b32 v2, v44, v45 offset1:1
	v_add_u32_e32 v2, 0x2cb0, v69
	s_waitcnt vmcnt(4)
	ds_write2_b32 v2, v46, v47 offset1:1
	v_add_u32_e32 v2, 0x2cb8, v69
	ds_write2_b32 v2, v48, v49 offset1:1
	v_add_u32_e32 v2, 0x30c0, v69
	s_waitcnt vmcnt(3)
	ds_write2_b32 v2, v50, v51 offset1:1
	v_add_u32_e32 v2, 0x30c8, v69
	ds_write2_b32 v2, v52, v53 offset1:1
	v_add_u32_e32 v2, 0x34d0, v69
	s_waitcnt vmcnt(2)
	ds_write2_b32 v2, v54, v55 offset1:1
	v_add_u32_e32 v2, 0x34d8, v69
	ds_write2_b32 v2, v56, v57 offset1:1
	v_add_u32_e32 v2, 0x38e0, v69
	s_waitcnt vmcnt(1)
	ds_write2_b32 v2, v58, v59 offset1:1
	v_add_u32_e32 v2, 0x38e8, v69
	ds_write2_b32 v2, v60, v61 offset1:1
	v_add_u32_e32 v2, 0x3cf0, v69
	s_waitcnt vmcnt(0)
	ds_write2_b32 v2, v62, v63 offset1:1
	v_add_u32_e32 v2, 0x3cf8, v69
	ds_write2_b32 v2, v64, v65 offset1:1
	s_waitcnt lgkmcnt(0)
	ds_read2_b32 v[6:7], v101 offset0:65 offset1:73
	ds_read2_b32 v[8:9], v101 offset1:8
	ds_read2_b32 v[10:11], v101 offset0:130 offset1:138
	ds_read2_b32 v[12:13], v101 offset0:195 offset1:203
	s_lshl_b32 s30, s6, 7
	s_and_b32 s5, s5, 0xffff
	s_waitcnt lgkmcnt(2)
; #define LAS __attribute__((address_space(3)))
; __device__ __forceinline__ unsigned pk2(float lo, float hi) { const f32x2_g v = {lo, hi}; return __builtin_bit_cast(unsigned, __builtin_convertvector(v, bf16x2_g)); }
; template <class RowMap>
; __device__ __forceinline__ void transpose_item(const float* W, int K, int N, int ldw, bf16_t* WT, const RowMap& rm, LAS float* scr, int item, int lane, const float* kscale = nullptr) {
;     ...
;     const int c = lane & 7;
; #pragma unroll
;     for (int j = 0; j < 8; ++j) { const int n = (lane >> 3) + 8 * j; const LAS float* s = scr + (8 * c) * 65 + n;
;         u32x4 o; o.x = pk2(s[0 * 65], s[1 * 65]); o.y = pk2(s[2 * 65], s[3 * 65]); o.z = pk2(s[4 * 65], s[5 * 65]); o.w = pk2(s[6 * 65], s[7 * 65]);
;         __builtin_nontemporal_store(o, (u32x4*)(WT + (size_t)rm(n0 + n) * K + k0 + 8 * c)); }
;     asm volatile("s_waitcnt lgkmcnt(0)" ::: "memory");
	v_cvt_pk_bf16_f32 v2, v8, v6
	v_or_b32_e32 v6, s4, v71
	s_cmpk_gt_u32 s5, 0x57
	v_add_u32_e32 v8, 0xffffea00, v6
	s_cselect_b64 vcc, -1, 0
	v_add_u32_e32 v26, 0x400, v101
	v_cndmask_b32_e32 v6, v6, v8, vcc
	ds_read2_b32 v[14:15], v26 offset0:4 offset1:12
	ds_read2_b32 v[16:17], v26 offset0:69 offset1:77
	ds_read2_b32 v[18:19], v26 offset0:134 offset1:142
	ds_read2_b32 v[20:21], v26 offset0:199 offset1:207
	v_lshlrev_b32_e32 v8, 1, v6
	s_and_b64 s[6:7], vcc, exec
	v_and_b32_e32 v8, 0xffffff00, v8
	s_cselect_b32 s5, 0x80, 0
	v_and_b32_e32 v6, 0x47, v6
	v_or3_b32 v24, v6, v8, s5
	v_ashrrev_i32_e32 v25, 31, v24
	v_lshl_add_u64 v[22:23], v[78:79], 0, s[30:31]
	v_lshlrev_b64 v[24:25], 12, v[24:25]
	s_waitcnt lgkmcnt(4)
	v_cvt_pk_bf16_f32 v3, v10, v12
	s_waitcnt lgkmcnt(2)
	v_cvt_pk_bf16_f32 v4, v14, v16
	s_waitcnt lgkmcnt(0)
	v_cvt_pk_bf16_f32 v5, v18, v20
	v_lshl_add_u64 v[24:25], v[22:23], 0, v[24:25]
	v_or_b32_e32 v6, s4, v103
	global_store_dwordx4 v[24:25], v[2:5], off nt
	s_nop 1
	v_cvt_pk_bf16_f32 v2, v9, v7
	v_add_u32_e32 v7, 0xffffea00, v6
	v_cndmask_b32_e32 v6, v6, v7, vcc
	v_lshlrev_b32_e32 v7, 1, v6
	v_and_b32_e32 v7, 0xffffff00, v7
	v_and_b32_e32 v6, 0x4f, v6
	v_or3_b32 v6, v6, v7, s5
	v_ashrrev_i32_e32 v7, 31, v6
	v_lshlrev_b64 v[6:7], 12, v[6:7]
	v_cvt_pk_bf16_f32 v3, v11, v13
	v_cvt_pk_bf16_f32 v4, v15, v17
	v_cvt_pk_bf16_f32 v5, v19, v21
	v_lshl_add_u64 v[6:7], v[22:23], 0, v[6:7]
	ds_read2_b32 v[8:9], v101 offset0:16 offset1:24
	ds_read2_b32 v[10:11], v101 offset0:81 offset1:89
	ds_read2_b32 v[12:13], v101 offset0:146 offset1:154
	ds_read2_b32 v[14:15], v101 offset0:211 offset1:219
	ds_read2_b32 v[16:17], v26 offset0:20 offset1:28
	ds_read2_b32 v[18:19], v26 offset0:85 offset1:93
	ds_read2_b32 v[20:21], v26 offset0:150 offset1:158
	ds_read2_b32 v[24:25], v26 offset0:215 offset1:223
	global_store_dwordx4 v[6:7], v[2:5], off nt
	v_or_b32_e32 v6, s4, v105
	v_add_u32_e32 v7, 0xffffea00, v6
	v_cndmask_b32_e32 v6, v6, v7, vcc
	v_lshlrev_b32_e32 v7, 1, v6
	v_and_b32_e32 v7, 0xffffff00, v7
	v_and_b32_e32 v6, 0x57, v6
	v_or3_b32 v6, v6, v7, s5
	v_ashrrev_i32_e32 v7, 31, v6
	v_lshlrev_b64 v[6:7], 12, v[6:7]
	s_waitcnt lgkmcnt(6)
	v_cvt_pk_bf16_f32 v2, v8, v10
	s_waitcnt lgkmcnt(4)
	v_cvt_pk_bf16_f32 v3, v12, v14
	s_waitcnt lgkmcnt(2)
	v_cvt_pk_bf16_f32 v4, v16, v18
	s_waitcnt lgkmcnt(0)
	v_cvt_pk_bf16_f32 v5, v20, v24
	v_lshl_add_u64 v[6:7], v[22:23], 0, v[6:7]
	global_store_dwordx4 v[6:7], v[2:5], off nt
	v_or_b32_e32 v6, s4, v107
	v_add_u32_e32 v7, 0xffffea00, v6
	v_cndmask_b32_e32 v6, v6, v7, vcc
	v_lshlrev_b32_e32 v7, 1, v6
	v_and_b32_e32 v7, 0xffffff00, v7
	v_and_b32_e32 v6, 0x5f, v6
	v_or3_b32 v6, v6, v7, s5
	v_ashrrev_i32_e32 v7, 31, v6
	v_lshlrev_b64 v[6:7], 12, v[6:7]
	v_cvt_pk_bf16_f32 v2, v9, v11
	v_cvt_pk_bf16_f32 v3, v13, v15
	v_cvt_pk_bf16_f32 v4, v17, v19
	v_cvt_pk_bf16_f32 v5, v21, v25
	v_lshl_add_u64 v[6:7], v[22:23], 0, v[6:7]
	ds_read2_b32 v[8:9], v101 offset0:32 offset1:40
	ds_read2_b32 v[10:11], v101 offset0:97 offset1:105
	ds_read2_b32 v[12:13], v101 offset0:162 offset1:170
	ds_read2_b32 v[14:15], v101 offset0:227 offset1:235
	ds_read2_b32 v[16:17], v26 offset0:36 offset1:44
	ds_read2_b32 v[18:19], v26 offset0:101 offset1:109
	ds_read2_b32 v[20:21], v26 offset0:166 offset1:174
	ds_read2_b32 v[24:25], v26 offset0:231 offset1:239
	global_store_dwordx4 v[6:7], v[2:5], off nt
	v_or_b32_e32 v6, s4, v109
	v_add_u32_e32 v7, 0xffffea00, v6
	v_cndmask_b32_e32 v6, v6, v7, vcc
	v_lshlrev_b32_e32 v7, 1, v6
	v_and_b32_e32 v7, 0xffffff00, v7
	v_and_b32_e32 v6, 0x67, v6
	v_or3_b32 v6, v6, v7, s5
	v_ashrrev_i32_e32 v7, 31, v6
	v_lshlrev_b64 v[6:7], 12, v[6:7]
	s_waitcnt lgkmcnt(6)
	v_cvt_pk_bf16_f32 v2, v8, v10
	s_waitcnt lgkmcnt(4)
	v_cvt_pk_bf16_f32 v3, v12, v14
	s_waitcnt lgkmcnt(2)
	v_cvt_pk_bf16_f32 v4, v16, v18
	s_waitcnt lgkmcnt(0)
	v_cvt_pk_bf16_f32 v5, v20, v24
	v_lshl_add_u64 v[6:7], v[22:23], 0, v[6:7]
	global_store_dwordx4 v[6:7], v[2:5], off nt
	v_or_b32_e32 v6, s4, v111
	v_add_u32_e32 v7, 0xffffea00, v6
	v_cndmask_b32_e32 v6, v6, v7, vcc
	v_lshlrev_b32_e32 v7, 1, v6
	v_and_b32_e32 v7, 0xffffff00, v7
	v_and_b32_e32 v6, 0x6f, v6
	v_or3_b32 v6, v6, v7, s5
	v_ashrrev_i32_e32 v7, 31, v6
	v_lshlrev_b64 v[6:7], 12, v[6:7]
	v_cvt_pk_bf16_f32 v2, v9, v11
	v_cvt_pk_bf16_f32 v3, v13, v15
	v_cvt_pk_bf16_f32 v4, v17, v19
	v_cvt_pk_bf16_f32 v5, v21, v25
	v_lshl_add_u64 v[6:7], v[22:23], 0, v[6:7]
	ds_read2_b32 v[8:9], v101 offset0:48 offset1:56
	ds_read2_b32 v[10:11], v101 offset0:113 offset1:121
	ds_read2_b32 v[12:13], v101 offset0:178 offset1:186
	ds_read2_b32 v[14:15], v101 offset0:243 offset1:251
	ds_read2_b32 v[16:17], v26 offset0:52 offset1:60
	ds_read2_b32 v[18:19], v26 offset0:117 offset1:125
	ds_read2_b32 v[20:21], v26 offset0:182 offset1:190
	ds_read2_b32 v[24:25], v26 offset0:247 offset1:255
	global_store_dwordx4 v[6:7], v[2:5], off nt
	v_or_b32_e32 v6, s4, v113
	v_add_u32_e32 v7, 0xffffea00, v6
	v_cndmask_b32_e32 v6, v6, v7, vcc
	v_lshlrev_b32_e32 v7, 1, v6
	v_and_b32_e32 v7, 0xffffff00, v7
	v_and_b32_e32 v6, 0x77, v6
	v_or3_b32 v6, v6, v7, s5
	v_ashrrev_i32_e32 v7, 31, v6
	v_lshlrev_b64 v[6:7], 12, v[6:7]
	s_waitcnt lgkmcnt(6)
	v_cvt_pk_bf16_f32 v2, v8, v10
	s_waitcnt lgkmcnt(4)
	v_cvt_pk_bf16_f32 v3, v12, v14
	s_waitcnt lgkmcnt(2)
	v_cvt_pk_bf16_f32 v4, v16, v18
	s_waitcnt lgkmcnt(0)
	v_cvt_pk_bf16_f32 v5, v20, v24
	v_lshl_add_u64 v[6:7], v[22:23], 0, v[6:7]
	global_store_dwordx4 v[6:7], v[2:5], off nt
	v_or_b32_e32 v6, s4, v115
	v_add_u32_e32 v7, 0xffffea00, v6
	v_cndmask_b32_e32 v6, v6, v7, vcc
	v_lshlrev_b32_e32 v7, 1, v6
	v_and_b32_e32 v7, 0xffffff00, v7
	v_and_b32_e32 v6, 0x7f, v6
	v_or3_b32 v6, v6, v7, s5
	v_ashrrev_i32_e32 v7, 31, v6
	v_lshlrev_b64 v[6:7], 12, v[6:7]
	v_cvt_pk_bf16_f32 v2, v9, v11
	v_cvt_pk_bf16_f32 v3, v13, v15
	v_cvt_pk_bf16_f32 v4, v17, v19
	v_cvt_pk_bf16_f32 v5, v21, v25
	v_lshl_add_u64 v[6:7], v[22:23], 0, v[6:7]
	global_store_dwordx4 v[6:7], v[2:5], off nt
	s_waitcnt lgkmcnt(0)

; template <class RowMap>
; __device__ __forceinline__ void transpose_item(const float* W, int K, int N, int ldw, bf16_t* WT, const RowMap& rm, LAS float* scr, int item, int lane, const float* kscale = nullptr) {
;     const int nblk = N / 64, kb = item / nblk, nb = item % nblk, k0 = 64 * kb, n0 = 64 * nb;
;     f32x4 v[16]; float ksc[16];
; #pragma unroll
;     for (int i = 0; i < 16; ++i) { const int kk = 4 * i + (lane >> 4), c4 = (lane & 15) * 4;
;         v[i] = __builtin_nontemporal_load((const f32x4*)(W + (size_t)(k0 + kk) * ldw + n0 + c4)); ksc[i] = kscale ? kscale[k0 + kk] : 1.0f; }
;     __builtin_amdgcn_sched_barrier(0);
; #pragma unroll
;     for (int i = 0; i < 16; ++i) { const int kk = 4 * i + (lane >> 4), c4 = (lane & 15) * 4; const f32x4 w = kscale ? v[i] * ksc[i] : v[i];
;         scr[kk * 65 + c4] = w[0]; scr[kk * 65 + c4 + 1] = w[1]; scr[kk * 65 + c4 + 2] = w[2]; scr[kk * 65 + c4 + 3] = w[3]; }
;     asm volatile("s_waitcnt lgkmcnt(0)" ::: "memory");
.LBB0_22:
	s_andn2_b64 vcc, exec, s[4:5]
	s_cbranch_vccnz .LBB0_24
	s_add_i32 s4, s28, 0x3400
	s_and_b32 s5, s4, 0x1ffc0
	s_and_b32 s4, s26, 0x7c0
	v_or_b32_e32 v4, s5, v67
	s_lshl_b32 s30, s4, 2
	v_lshl_add_u64 v[2:3], v[80:81], 0, s[30:31]
	v_lshlrev_b32_e32 v178, 13, v4
	v_lshl_add_u64 v[58:59], v[2:3], 0, v[178:179]
	v_add_co_u32_e32 v6, vcc, 0x8000, v58
	s_nop 1
	v_addc_co_u32_e32 v7, vcc, 0, v59, vcc
	v_add_co_u32_e32 v10, vcc, 0x10000, v58
	global_load_dwordx4 v[2:5], v[58:59], off nt
	s_nop 0
	global_load_dwordx4 v[6:9], v[6:7], off nt
	v_addc_co_u32_e32 v11, vcc, 0, v59, vcc
	v_add_co_u32_e32 v14, vcc, 0x18000, v58
	s_nop 1
	v_addc_co_u32_e32 v15, vcc, 0, v59, vcc
	v_add_co_u32_e32 v18, vcc, 0x20000, v58
	global_load_dwordx4 v[10:13], v[10:11], off nt
	s_nop 0
	global_load_dwordx4 v[14:17], v[14:15], off nt
	v_addc_co_u32_e32 v19, vcc, 0, v59, vcc
	v_add_co_u32_e32 v22, vcc, 0x28000, v58
	s_nop 1
	v_addc_co_u32_e32 v23, vcc, 0, v59, vcc
	v_add_co_u32_e32 v26, vcc, 0x30000, v58
	global_load_dwordx4 v[18:21], v[18:19], off nt
	s_nop 0
	global_load_dwordx4 v[22:25], v[22:23], off nt
	v_addc_co_u32_e32 v27, vcc, 0, v59, vcc
	v_add_co_u32_e32 v30, vcc, 0x38000, v58
	s_nop 1
	v_addc_co_u32_e32 v31, vcc, 0, v59, vcc
	v_add_co_u32_e32 v34, vcc, 0x40000, v58
	global_load_dwordx4 v[26:29], v[26:27], off nt
	s_nop 0
	global_load_dwordx4 v[30:33], v[30:31], off nt
	v_addc_co_u32_e32 v35, vcc, 0, v59, vcc
	v_add_co_u32_e32 v38, vcc, 0x48000, v58
	s_nop 1
	v_addc_co_u32_e32 v39, vcc, 0, v59, vcc
	v_add_co_u32_e32 v42, vcc, 0x50000, v58
	global_load_dwordx4 v[34:37], v[34:35], off nt
	s_nop 0
	global_load_dwordx4 v[38:41], v[38:39], off nt
	v_addc_co_u32_e32 v43, vcc, 0, v59, vcc
	v_add_co_u32_e32 v46, vcc, 0x58000, v58
	s_nop 1
	v_addc_co_u32_e32 v47, vcc, 0, v59, vcc
	v_add_co_u32_e32 v50, vcc, 0x60000, v58
	global_load_dwordx4 v[42:45], v[42:43], off nt
	s_nop 0
	global_load_dwordx4 v[46:49], v[46:47], off nt
	v_addc_co_u32_e32 v51, vcc, 0, v59, vcc
	v_add_co_u32_e32 v54, vcc, 0x68000, v58
	s_nop 1
	v_addc_co_u32_e32 v55, vcc, 0, v59, vcc
	v_add_co_u32_e32 v60, vcc, 0x70000, v58
	global_load_dwordx4 v[50:53], v[50:51], off nt
	s_nop 0
	global_load_dwordx4 v[54:57], v[54:55], off nt
	v_addc_co_u32_e32 v61, vcc, 0, v59, vcc
	v_add_co_u32_e32 v62, vcc, 0x78000, v58
	s_nop 1
	v_addc_co_u32_e32 v63, vcc, 0, v59, vcc
	global_load_dwordx4 v[58:61], v[60:61], off nt
	s_nop 0
	global_load_dwordx4 v[62:65], v[62:63], off nt
	s_waitcnt vmcnt(15)
	ds_write2_b32 v69, v2, v3 offset1:1
	ds_write2_b32 v69, v4, v5 offset0:2 offset1:3
	v_add_u32_e32 v2, 0x410, v69
	s_waitcnt vmcnt(14)
	ds_write2_b32 v2, v6, v7 offset1:1
	v_add_u32_e32 v2, 0x418, v69
	ds_write2_b32 v2, v8, v9 offset1:1
	v_add_u32_e32 v2, 0x820, v69
	s_waitcnt vmcnt(13)
	ds_write2_b32 v2, v10, v11 offset1:1
	v_add_u32_e32 v2, 0x828, v69
	ds_write2_b32 v2, v12, v13 offset1:1
	v_add_u32_e32 v2, 0xc30, v69
	s_waitcnt vmcnt(12)
	ds_write2_b32 v2, v14, v15 offset1:1
	v_add_u32_e32 v2, 0xc38, v69
	ds_write2_b32 v2, v16, v17 offset1:1
	v_add_u32_e32 v2, 0x1040, v69
	s_waitcnt vmcnt(11)
	ds_write2_b32 v2, v18, v19 offset1:1
	v_add_u32_e32 v2, 0x1048, v69
	ds_write2_b32 v2, v20, v21 offset1:1
	v_add_u32_e32 v2, 0x1450, v69
	s_waitcnt vmcnt(10)
	ds_write2_b32 v2, v22, v23 offset1:1
	v_add_u32_e32 v2, 0x1458, v69
	ds_write2_b32 v2, v24, v25 offset1:1
	v_add_u32_e32 v2, 0x1860, v69
	s_waitcnt vmcnt(9)
	ds_write2_b32 v2, v26, v27 offset1:1
	v_add_u32_e32 v2, 0x1868, v69
	ds_write2_b32 v2, v28, v29 offset1:1
	v_add_u32_e32 v2, 0x1c70, v69
	s_waitcnt vmcnt(8)
	ds_write2_b32 v2, v30, v31 offset1:1
	v_add_u32_e32 v2, 0x1c78, v69
	ds_write2_b32 v2, v32, v33 offset1:1
	v_add_u32_e32 v2, 0x2080, v69
	s_waitcnt vmcnt(7)
	ds_write2_b32 v2, v34, v35 offset1:1
	v_add_u32_e32 v2, 0x2088, v69
	ds_write2_b32 v2, v36, v37 offset1:1
	v_add_u32_e32 v2, 0x2490, v69
	s_waitcnt vmcnt(6)
	ds_write2_b32 v2, v38, v39 offset1:1
	v_add_u32_e32 v2, 0x2498, v69
	ds_write2_b32 v2, v40, v41 offset1:1
	v_add_u32_e32 v2, 0x28a0, v69
	s_waitcnt vmcnt(5)
	ds_write2_b32 v2, v42, v43 offset1:1
	v_add_u32_e32 v2, 0x28a8, v69
	ds_write2_b32 v2, v44, v45 offset1:1
	v_add_u32_e32 v2, 0x2cb0, v69
	s_waitcnt vmcnt(4)
	ds_write2_b32 v2, v46, v47 offset1:1
	v_add_u32_e32 v2, 0x2cb8, v69
	ds_write2_b32 v2, v48, v49 offset1:1
	v_add_u32_e32 v2, 0x30c0, v69
	s_waitcnt vmcnt(3)
	ds_write2_b32 v2, v50, v51 offset1:1
	v_add_u32_e32 v2, 0x30c8, v69
	ds_write2_b32 v2, v52, v53 offset1:1
	v_add_u32_e32 v2, 0x34d0, v69
	s_waitcnt vmcnt(2)
	ds_write2_b32 v2, v54, v55 offset1:1
	v_add_u32_e32 v2, 0x34d8, v69
	ds_write2_b32 v2, v56, v57 offset1:1
	v_add_u32_e32 v2, 0x38e0, v69
	s_waitcnt vmcnt(1)
; #define LAS __attribute__((address_space(3)))
; __device__ __forceinline__ unsigned pk2(float lo, float hi) { const f32x2_g v = {lo, hi}; return __builtin_bit_cast(unsigned, __builtin_convertvector(v, bf16x2_g)); }
; template <class RowMap>
; __device__ __forceinline__ void transpose_item(const float* W, int K, int N, int ldw, bf16_t* WT, const RowMap& rm, LAS float* scr, int item, int lane, const float* kscale = nullptr) {
;     ...
;         scr[kk * 65 + c4] = w[0]; scr[kk * 65 + c4 + 1] = w[1]; scr[kk * 65 + c4 + 2] = w[2]; scr[kk * 65 + c4 + 3] = w[3]; }
;     asm volatile("s_waitcnt lgkmcnt(0)" ::: "memory");
;     const int c = lane & 7;
; #pragma unroll
;     for (int j = 0; j < 8; ++j) { const int n = (lane >> 3) + 8 * j; const LAS float* s = scr + (8 * c) * 65 + n;
;         u32x4 o; o.x = pk2(s[0 * 65], s[1 * 65]); o.y = pk2(s[2 * 65], s[3 * 65]); o.z = pk2(s[4 * 65], s[5 * 65]); o.w = pk2(s[6 * 65], s[7 * 65]);
;         __builtin_nontemporal_store(o, (u32x4*)(WT + (size_t)rm(n0 + n) * K + k0 + 8 * c)); }
;     asm volatile("s_waitcnt lgkmcnt(0)" ::: "memory");
	ds_write2_b32 v2, v58, v59 offset1:1
	v_add_u32_e32 v2, 0x38e8, v69
	ds_write2_b32 v2, v60, v61 offset1:1
	v_add_u32_e32 v2, 0x3cf0, v69
	s_waitcnt vmcnt(0)
	ds_write2_b32 v2, v62, v63 offset1:1
	v_add_u32_e32 v2, 0x3cf8, v69
	ds_write2_b32 v2, v64, v65 offset1:1
	s_waitcnt lgkmcnt(0)
	v_add_u32_e32 v26, 0x400, v101
	ds_read2_b32 v[6:7], v101 offset0:65 offset1:73
	ds_read2_b32 v[8:9], v101 offset1:8
	ds_read2_b32 v[10:11], v101 offset0:130 offset1:138
	ds_read2_b32 v[12:13], v101 offset0:195 offset1:203
	ds_read2_b32 v[14:15], v26 offset0:4 offset1:12
	ds_read2_b32 v[16:17], v26 offset0:69 offset1:77
	ds_read2_b32 v[18:19], v26 offset0:134 offset1:142
	ds_read2_b32 v[20:21], v26 offset0:199 offset1:207
	s_lshl_b32 s30, s5, 1
	s_waitcnt lgkmcnt(6)
	v_cvt_pk_bf16_f32 v2, v8, v6
	v_or_b32_e32 v6, s4, v71
	v_lshl_add_u64 v[22:23], v[82:83], 0, s[30:31]
	v_lshlrev_b32_e32 v178, 12, v6
	s_waitcnt lgkmcnt(4)
	v_cvt_pk_bf16_f32 v3, v10, v12
	s_waitcnt lgkmcnt(2)
	v_cvt_pk_bf16_f32 v4, v14, v16
	s_waitcnt lgkmcnt(0)
	v_cvt_pk_bf16_f32 v5, v18, v20
	v_lshl_add_u64 v[24:25], v[22:23], 0, v[178:179]
	global_store_dwordx4 v[24:25], v[2:5], off nt
	v_or_b32_e32 v6, s4, v103
	v_lshlrev_b32_e32 v178, 12, v6
	v_cvt_pk_bf16_f32 v2, v9, v7
	v_cvt_pk_bf16_f32 v3, v11, v13
	v_cvt_pk_bf16_f32 v4, v15, v17
	v_cvt_pk_bf16_f32 v5, v19, v21
	ds_read2_b32 v[8:9], v101 offset0:81 offset1:89
	ds_read2_b32 v[10:11], v101 offset0:16 offset1:24
	ds_read2_b32 v[12:13], v101 offset0:146 offset1:154
	ds_read2_b32 v[14:15], v101 offset0:211 offset1:219
	ds_read2_b32 v[16:17], v26 offset0:20 offset1:28
	ds_read2_b32 v[18:19], v26 offset0:85 offset1:93
	ds_read2_b32 v[20:21], v26 offset0:150 offset1:158
	ds_read2_b32 v[24:25], v26 offset0:215 offset1:223
	v_lshl_add_u64 v[6:7], v[22:23], 0, v[178:179]
	global_store_dwordx4 v[6:7], v[2:5], off nt
	v_or_b32_e32 v6, s4, v105
	v_lshlrev_b32_e32 v178, 12, v6
	s_waitcnt lgkmcnt(6)
	v_cvt_pk_bf16_f32 v2, v10, v8
	s_waitcnt lgkmcnt(4)
	v_cvt_pk_bf16_f32 v3, v12, v14
	s_waitcnt lgkmcnt(2)
	v_cvt_pk_bf16_f32 v4, v16, v18
	s_waitcnt lgkmcnt(0)
	v_cvt_pk_bf16_f32 v5, v20, v24
	v_lshl_add_u64 v[6:7], v[22:23], 0, v[178:179]
	global_store_dwordx4 v[6:7], v[2:5], off nt
	v_or_b32_e32 v6, s4, v107
	v_lshlrev_b32_e32 v178, 12, v6
	v_cvt_pk_bf16_f32 v2, v11, v9
	v_cvt_pk_bf16_f32 v3, v13, v15
	v_cvt_pk_bf16_f32 v4, v17, v19
	v_cvt_pk_bf16_f32 v5, v21, v25
	ds_read2_b32 v[8:9], v101 offset0:32 offset1:40
	ds_read2_b32 v[10:11], v101 offset0:97 offset1:105
	ds_read2_b32 v[12:13], v101 offset0:162 offset1:170
	ds_read2_b32 v[14:15], v101 offset0:227 offset1:235
	ds_read2_b32 v[16:17], v26 offset0:36 offset1:44
	ds_read2_b32 v[18:19], v26 offset0:101 offset1:109
	ds_read2_b32 v[20:21], v26 offset0:166 offset1:174
	ds_read2_b32 v[24:25], v26 offset0:231 offset1:239
	v_lshl_add_u64 v[6:7], v[22:23], 0, v[178:179]
	global_store_dwordx4 v[6:7], v[2:5], off nt
	v_or_b32_e32 v6, s4, v109
	v_lshlrev_b32_e32 v178, 12, v6
	s_waitcnt lgkmcnt(6)
	v_cvt_pk_bf16_f32 v2, v8, v10
	s_waitcnt lgkmcnt(4)
	v_cvt_pk_bf16_f32 v3, v12, v14
	s_waitcnt lgkmcnt(2)
	v_cvt_pk_bf16_f32 v4, v16, v18
	s_waitcnt lgkmcnt(0)
	v_cvt_pk_bf16_f32 v5, v20, v24
	v_lshl_add_u64 v[6:7], v[22:23], 0, v[178:179]
	global_store_dwordx4 v[6:7], v[2:5], off nt
	v_or_b32_e32 v6, s4, v111
	v_lshlrev_b32_e32 v178, 12, v6
	v_cvt_pk_bf16_f32 v2, v9, v11
	v_cvt_pk_bf16_f32 v3, v13, v15
	v_cvt_pk_bf16_f32 v4, v17, v19
	v_cvt_pk_bf16_f32 v5, v21, v25
	ds_read2_b32 v[8:9], v101 offset0:48 offset1:56
	ds_read2_b32 v[10:11], v101 offset0:113 offset1:121
	ds_read2_b32 v[12:13], v101 offset0:178 offset1:186
	ds_read2_b32 v[14:15], v101 offset0:243 offset1:251
	ds_read2_b32 v[16:17], v26 offset0:52 offset1:60
	ds_read2_b32 v[18:19], v26 offset0:117 offset1:125
	ds_read2_b32 v[20:21], v26 offset0:182 offset1:190
	ds_read2_b32 v[24:25], v26 offset0:247 offset1:255
	v_lshl_add_u64 v[6:7], v[22:23], 0, v[178:179]
	global_store_dwordx4 v[6:7], v[2:5], off nt
	v_or_b32_e32 v6, s4, v113
	v_lshlrev_b32_e32 v178, 12, v6
	s_waitcnt lgkmcnt(6)
	v_cvt_pk_bf16_f32 v2, v8, v10
	s_waitcnt lgkmcnt(4)
	v_cvt_pk_bf16_f32 v3, v12, v14
	s_waitcnt lgkmcnt(2)
	v_cvt_pk_bf16_f32 v4, v16, v18
	s_waitcnt lgkmcnt(0)
	v_cvt_pk_bf16_f32 v5, v20, v24
	v_lshl_add_u64 v[6:7], v[22:23], 0, v[178:179]
	global_store_dwordx4 v[6:7], v[2:5], off nt
	v_or_b32_e32 v6, s4, v115
	v_lshlrev_b32_e32 v178, 12, v6
	v_cvt_pk_bf16_f32 v2, v9, v11
	v_cvt_pk_bf16_f32 v3, v13, v15
	v_cvt_pk_bf16_f32 v4, v17, v19
	v_cvt_pk_bf16_f32 v5, v21, v25
	v_lshl_add_u64 v[6:7], v[22:23], 0, v[178:179]
	global_store_dwordx4 v[6:7], v[2:5], off nt
	s_waitcnt lgkmcnt(0)

; template <class RowMap>
; __device__ __forceinline__ void transpose_item(const float* W, int K, int N, int ldw, bf16_t* WT, const RowMap& rm, LAS float* scr, int item, int lane, const float* kscale = nullptr) {
;     const int nblk = N / 64, kb = item / nblk, nb = item % nblk, k0 = 64 * kb, n0 = 64 * nb;
;     f32x4 v[16]; float ksc[16];
; #pragma unroll
;     for (int i = 0; i < 16; ++i) { const int kk = 4 * i + (lane >> 4), c4 = (lane & 15) * 4;
;         v[i] = __builtin_nontemporal_load((const f32x4*)(W + (size_t)(k0 + kk) * ldw + n0 + c4)); ksc[i] = kscale ? kscale[k0 + kk] : 1.0f; }
;     __builtin_amdgcn_sched_barrier(0);
; #pragma unroll
;     for (int i = 0; i < 16; ++i) { const int kk = 4 * i + (lane >> 4), c4 = (lane & 15) * 4; const f32x4 w = kscale ? v[i] * ksc[i] : v[i];
;         scr[kk * 65 + c4] = w[0]; scr[kk * 65 + c4 + 1] = w[1]; scr[kk * 65 + c4 + 2] = w[2]; scr[kk * 65 + c4 + 3] = w[3]; }
;     asm volatile("s_waitcnt lgkmcnt(0)" ::: "memory");
; __global__ void __launch_bounds__(512, 2) mk_fwd(Args args) {
;     ...
;                 if (r < 3 * I_BR) { const int n = r / I_BR; transpose_item(w_br + (size_t)n * 1024 * DM, 1024, DM, DM, WB + WE_BR + (size_t)n * DM * 1024, RowId{0}, scr, r - n * I_BR, lane); continue; } r -= 3 * I_BR;
.LBB0_25:
	s_andn2_b64 vcc, exec, s[4:5]
	s_cbranch_vccnz .LBB0_27
	s_add_i32 s4, s0, 0xffffe620
	s_lshr_b32 s30, s4, 9
	s_lshl_b64 s[4:5], s[30:31], 23
	s_add_u32 s6, s1, s4
	s_addc_u32 s7, s9, s5
	s_lshl_b64 s[4:5], s[30:31], 22
	s_add_u32 s20, s24, s4
	s_addc_u32 s5, s25, s5
	s_add_i32 s4, s28, 0xfffe4000
	s_and_b32 s21, s4, 0x3c0
	s_and_b32 s4, s26, 0x7c0
	s_lshl_b32 s22, s4, 2
	s_add_u32 s6, s6, s22
	v_or_b32_e32 v4, s21, v67
	s_addc_u32 s7, s7, 0
	v_mov_b32_e32 v97, v179
	v_lshl_add_u64 v[2:3], s[6:7], 0, v[96:97]
	v_lshlrev_b32_e32 v178, 13, v4
	v_lshl_add_u64 v[58:59], v[2:3], 0, v[178:179]
	s_mov_b32 s6, 0x8000
	v_add_co_u32_e32 v6, vcc, s6, v58
	s_mov_b32 s6, 0x10000
	s_nop 0
	v_addc_co_u32_e32 v7, vcc, 0, v59, vcc
	v_add_co_u32_e32 v10, vcc, s6, v58
	s_mov_b32 s6, 0x28000
	s_nop 0
	v_addc_co_u32_e32 v11, vcc, 0, v59, vcc
	v_add_co_u32_e32 v14, vcc, s94, v58
	global_load_dwordx4 v[2:5], v[58:59], off nt
	s_nop 0
	global_load_dwordx4 v[6:9], v[6:7], off nt
	v_addc_co_u32_e32 v15, vcc, 0, v59, vcc
	v_add_co_u32_e32 v18, vcc, s19, v58
	global_load_dwordx4 v[10:13], v[10:11], off nt
	s_nop 0
	global_load_dwordx4 v[14:17], v[14:15], off nt
	v_addc_co_u32_e32 v19, vcc, 0, v59, vcc
	v_add_co_u32_e32 v22, vcc, s6, v58
	s_mov_b32 s6, 0x38000
	s_nop 0
	v_addc_co_u32_e32 v23, vcc, 0, v59, vcc
	v_add_co_u32_e32 v26, vcc, s95, v58
	global_load_dwordx4 v[18:21], v[18:19], off nt
	s_nop 0
	global_load_dwordx4 v[22:25], v[22:23], off nt
	v_addc_co_u32_e32 v27, vcc, 0, v59, vcc
	v_add_co_u32_e32 v30, vcc, s6, v58
	s_mov_b32 s6, 0x40000
	s_nop 0
	v_addc_co_u32_e32 v31, vcc, 0, v59, vcc
	v_add_co_u32_e32 v34, vcc, s6, v58
	s_mov_b32 s6, 0x50000
	s_nop 0
	v_addc_co_u32_e32 v35, vcc, 0, v59, vcc
	v_add_co_u32_e32 v38, vcc, s41, v58
	global_load_dwordx4 v[26:29], v[26:27], off nt
	s_nop 0
	global_load_dwordx4 v[30:33], v[30:31], off nt
	v_addc_co_u32_e32 v39, vcc, 0, v59, vcc
	v_add_co_u32_e32 v42, vcc, s6, v58
	s_mov_b32 s6, 0x58000
	s_nop 0
	v_addc_co_u32_e32 v43, vcc, 0, v59, vcc
	v_add_co_u32_e32 v46, vcc, s6, v58
	s_mov_b32 s6, 0x60000
	s_nop 0
	v_addc_co_u32_e32 v47, vcc, 0, v59, vcc
	v_add_co_u32_e32 v50, vcc, s6, v58
	s_mov_b32 s6, 0x68000
	s_nop 0
	v_addc_co_u32_e32 v51, vcc, 0, v59, vcc
	v_add_co_u32_e32 v54, vcc, s6, v58
	s_mov_b32 s6, 0x70000
	s_nop 0
	v_addc_co_u32_e32 v55, vcc, 0, v59, vcc
	v_add_co_u32_e32 v60, vcc, s6, v58
	s_mov_b32 s6, 0x78000
	s_nop 0
	v_addc_co_u32_e32 v61, vcc, 0, v59, vcc
	v_add_co_u32_e32 v62, vcc, s6, v58
	global_load_dwordx4 v[34:37], v[34:35], off nt
	s_nop 0
	global_load_dwordx4 v[38:41], v[38:39], off nt
	v_addc_co_u32_e32 v63, vcc, 0, v59, vcc
	global_load_dwordx4 v[42:45], v[42:43], off nt
	s_nop 0
	global_load_dwordx4 v[46:49], v[46:47], off nt
	s_nop 0
	global_load_dwordx4 v[50:53], v[50:51], off nt
	s_nop 0
	global_load_dwordx4 v[54:57], v[54:55], off nt
	s_nop 0
	global_load_dwordx4 v[58:61], v[60:61], off nt
	s_nop 0
	global_load_dwordx4 v[62:65], v[62:63], off nt
	s_waitcnt vmcnt(15)
	ds_write2_b32 v69, v2, v3 offset1:1
	ds_write2_b32 v69, v4, v5 offset0:2 offset1:3
	v_add_u32_e32 v2, 0x410, v69
	s_waitcnt vmcnt(14)
	ds_write2_b32 v2, v6, v7 offset1:1
	v_add_u32_e32 v2, 0x418, v69
	ds_write2_b32 v2, v8, v9 offset1:1
	v_add_u32_e32 v2, 0x820, v69
	s_waitcnt vmcnt(13)
	ds_write2_b32 v2, v10, v11 offset1:1
	v_add_u32_e32 v2, 0x828, v69
	ds_write2_b32 v2, v12, v13 offset1:1
	v_add_u32_e32 v2, 0xc30, v69
	s_waitcnt vmcnt(12)
	ds_write2_b32 v2, v14, v15 offset1:1
	v_add_u32_e32 v2, 0xc38, v69
	ds_write2_b32 v2, v16, v17 offset1:1
	v_add_u32_e32 v2, 0x1040, v69
	s_waitcnt vmcnt(11)
	ds_write2_b32 v2, v18, v19 offset1:1
	v_add_u32_e32 v2, 0x1048, v69
	ds_write2_b32 v2, v20, v21 offset1:1
	v_add_u32_e32 v2, 0x1450, v69
	s_waitcnt vmcnt(10)
	ds_write2_b32 v2, v22, v23 offset1:1
	v_add_u32_e32 v2, 0x1458, v69
	ds_write2_b32 v2, v24, v25 offset1:1
	v_add_u32_e32 v2, 0x1860, v69
	s_waitcnt vmcnt(9)
	ds_write2_b32 v2, v26, v27 offset1:1
	v_add_u32_e32 v2, 0x1868, v69
	ds_write2_b32 v2, v28, v29 offset1:1
	v_add_u32_e32 v2, 0x1c70, v69
	s_waitcnt vmcnt(8)
	ds_write2_b32 v2, v30, v31 offset1:1
	v_add_u32_e32 v2, 0x1c78, v69
	ds_write2_b32 v2, v32, v33 offset1:1
	v_add_u32_e32 v2, 0x2080, v69
	s_waitcnt vmcnt(7)
	ds_write2_b32 v2, v34, v35 offset1:1
	v_add_u32_e32 v2, 0x2088, v69
	ds_write2_b32 v2, v36, v37 offset1:1
	v_add_u32_e32 v2, 0x2490, v69
	s_waitcnt vmcnt(6)
	ds_write2_b32 v2, v38, v39 offset1:1
	v_add_u32_e32 v2, 0x2498, v69
	ds_write2_b32 v2, v40, v41 offset1:1
	v_add_u32_e32 v2, 0x28a0, v69
	s_waitcnt vmcnt(5)
	ds_write2_b32 v2, v42, v43 offset1:1
	v_add_u32_e32 v2, 0x28a8, v69
	ds_write2_b32 v2, v44, v45 offset1:1
	v_add_u32_e32 v2, 0x2cb0, v69
	s_waitcnt vmcnt(4)
	ds_write2_b32 v2, v46, v47 offset1:1
	v_add_u32_e32 v2, 0x2cb8, v69
	ds_write2_b32 v2, v48, v49 offset1:1
	v_add_u32_e32 v2, 0x30c0, v69
	s_waitcnt vmcnt(3)
	ds_write2_b32 v2, v50, v51 offset1:1
	v_add_u32_e32 v2, 0x30c8, v69
	ds_write2_b32 v2, v52, v53 offset1:1
	v_add_u32_e32 v2, 0x34d0, v69
	s_waitcnt vmcnt(2)
; #define LAS __attribute__((address_space(3)))
; __device__ __forceinline__ unsigned pk2(float lo, float hi) { const f32x2_g v = {lo, hi}; return __builtin_bit_cast(unsigned, __builtin_convertvector(v, bf16x2_g)); }
; template <class RowMap>
; __device__ __forceinline__ void transpose_item(const float* W, int K, int N, int ldw, bf16_t* WT, const RowMap& rm, LAS float* scr, int item, int lane, const float* kscale = nullptr) {
;     ...
;     asm volatile("s_waitcnt lgkmcnt(0)" ::: "memory");
;     const int c = lane & 7;
; #pragma unroll
;     for (int j = 0; j < 8; ++j) { const int n = (lane >> 3) + 8 * j; const LAS float* s = scr + (8 * c) * 65 + n;
;         u32x4 o; o.x = pk2(s[0 * 65], s[1 * 65]); o.y = pk2(s[2 * 65], s[3 * 65]); o.z = pk2(s[4 * 65], s[5 * 65]); o.w = pk2(s[6 * 65], s[7 * 65]);
;         __builtin_nontemporal_store(o, (u32x4*)(WT + (size_t)rm(n0 + n) * K + k0 + 8 * c)); }
;     asm volatile("s_waitcnt lgkmcnt(0)" ::: "memory");
	ds_write2_b32 v2, v54, v55 offset1:1
	v_add_u32_e32 v2, 0x34d8, v69
	ds_write2_b32 v2, v56, v57 offset1:1
	v_add_u32_e32 v2, 0x38e0, v69
	s_waitcnt vmcnt(1)
	ds_write2_b32 v2, v58, v59 offset1:1
	v_add_u32_e32 v2, 0x38e8, v69
	ds_write2_b32 v2, v60, v61 offset1:1
	v_add_u32_e32 v2, 0x3cf0, v69
	s_waitcnt vmcnt(0)
	ds_write2_b32 v2, v62, v63 offset1:1
	v_add_u32_e32 v2, 0x3cf8, v69
	ds_write2_b32 v2, v64, v65 offset1:1
	s_waitcnt lgkmcnt(0)
	v_add_u32_e32 v26, 0x400, v101
	ds_read2_b32 v[6:7], v101 offset0:65 offset1:73
	ds_read2_b32 v[8:9], v101 offset1:8
	ds_read2_b32 v[10:11], v101 offset0:130 offset1:138
	ds_read2_b32 v[12:13], v101 offset0:195 offset1:203
	ds_read2_b32 v[14:15], v26 offset0:4 offset1:12
	ds_read2_b32 v[16:17], v26 offset0:69 offset1:77
	ds_read2_b32 v[18:19], v26 offset0:134 offset1:142
	ds_read2_b32 v[20:21], v26 offset0:199 offset1:207
	s_lshl_b32 s6, s21, 1
	s_add_u32 s6, s20, s6
	s_addc_u32 s7, s5, 0
	v_mov_b32_e32 v99, v179
	s_waitcnt lgkmcnt(6)
	v_cvt_pk_bf16_f32 v2, v8, v6
	v_or_b32_e32 v6, s4, v71
	v_lshl_add_u64 v[22:23], s[6:7], 0, v[98:99]
	v_lshlrev_b32_e32 v178, 11, v6
	s_waitcnt lgkmcnt(4)
	v_cvt_pk_bf16_f32 v3, v10, v12
	s_waitcnt lgkmcnt(2)
	v_cvt_pk_bf16_f32 v4, v14, v16
	s_waitcnt lgkmcnt(0)
	v_cvt_pk_bf16_f32 v5, v18, v20
	v_lshl_add_u64 v[24:25], v[22:23], 0, v[178:179]
	global_store_dwordx4 v[24:25], v[2:5], off nt
	v_or_b32_e32 v6, s4, v103
	v_lshlrev_b32_e32 v178, 11, v6
	v_cvt_pk_bf16_f32 v2, v9, v7
	v_cvt_pk_bf16_f32 v3, v11, v13
	v_cvt_pk_bf16_f32 v4, v15, v17
	v_cvt_pk_bf16_f32 v5, v19, v21
	ds_read2_b32 v[8:9], v101 offset0:81 offset1:89
	ds_read2_b32 v[10:11], v101 offset0:16 offset1:24
	ds_read2_b32 v[12:13], v101 offset0:146 offset1:154
	ds_read2_b32 v[14:15], v101 offset0:211 offset1:219
	ds_read2_b32 v[16:17], v26 offset0:20 offset1:28
	ds_read2_b32 v[18:19], v26 offset0:85 offset1:93
	ds_read2_b32 v[20:21], v26 offset0:150 offset1:158
	ds_read2_b32 v[24:25], v26 offset0:215 offset1:223
	v_lshl_add_u64 v[6:7], v[22:23], 0, v[178:179]
	global_store_dwordx4 v[6:7], v[2:5], off nt
	v_or_b32_e32 v6, s4, v105
	v_lshlrev_b32_e32 v178, 11, v6
	s_waitcnt lgkmcnt(6)
	v_cvt_pk_bf16_f32 v2, v10, v8
	s_waitcnt lgkmcnt(4)
	v_cvt_pk_bf16_f32 v3, v12, v14
	s_waitcnt lgkmcnt(2)
	v_cvt_pk_bf16_f32 v4, v16, v18
	s_waitcnt lgkmcnt(0)
	v_cvt_pk_bf16_f32 v5, v20, v24
	v_lshl_add_u64 v[6:7], v[22:23], 0, v[178:179]
	global_store_dwordx4 v[6:7], v[2:5], off nt
	v_or_b32_e32 v6, s4, v107
	v_lshlrev_b32_e32 v178, 11, v6
	v_cvt_pk_bf16_f32 v2, v11, v9
	v_cvt_pk_bf16_f32 v3, v13, v15
	v_cvt_pk_bf16_f32 v4, v17, v19
	v_cvt_pk_bf16_f32 v5, v21, v25
	ds_read2_b32 v[8:9], v101 offset0:32 offset1:40
	ds_read2_b32 v[10:11], v101 offset0:97 offset1:105
	ds_read2_b32 v[12:13], v101 offset0:162 offset1:170
	ds_read2_b32 v[14:15], v101 offset0:227 offset1:235
	ds_read2_b32 v[16:17], v26 offset0:36 offset1:44
	ds_read2_b32 v[18:19], v26 offset0:101 offset1:109
	ds_read2_b32 v[20:21], v26 offset0:166 offset1:174
	ds_read2_b32 v[24:25], v26 offset0:231 offset1:239
	v_lshl_add_u64 v[6:7], v[22:23], 0, v[178:179]
	global_store_dwordx4 v[6:7], v[2:5], off nt
	v_or_b32_e32 v6, s4, v109
	v_lshlrev_b32_e32 v178, 11, v6
	s_waitcnt lgkmcnt(6)
	v_cvt_pk_bf16_f32 v2, v8, v10
	s_waitcnt lgkmcnt(4)
	v_cvt_pk_bf16_f32 v3, v12, v14
	s_waitcnt lgkmcnt(2)
	v_cvt_pk_bf16_f32 v4, v16, v18
	s_waitcnt lgkmcnt(0)
	v_cvt_pk_bf16_f32 v5, v20, v24
	v_lshl_add_u64 v[6:7], v[22:23], 0, v[178:179]
	global_store_dwordx4 v[6:7], v[2:5], off nt
	v_or_b32_e32 v6, s4, v111
	v_lshlrev_b32_e32 v178, 11, v6
	v_cvt_pk_bf16_f32 v2, v9, v11
	v_cvt_pk_bf16_f32 v3, v13, v15
	v_cvt_pk_bf16_f32 v4, v17, v19
	v_cvt_pk_bf16_f32 v5, v21, v25
	ds_read2_b32 v[8:9], v101 offset0:48 offset1:56
	ds_read2_b32 v[10:11], v101 offset0:113 offset1:121
	ds_read2_b32 v[12:13], v101 offset0:178 offset1:186
	ds_read2_b32 v[14:15], v101 offset0:243 offset1:251
	ds_read2_b32 v[16:17], v26 offset0:52 offset1:60
	ds_read2_b32 v[18:19], v26 offset0:117 offset1:125
	ds_read2_b32 v[20:21], v26 offset0:182 offset1:190
	ds_read2_b32 v[24:25], v26 offset0:247 offset1:255
	v_lshl_add_u64 v[6:7], v[22:23], 0, v[178:179]
	global_store_dwordx4 v[6:7], v[2:5], off nt
	v_or_b32_e32 v6, s4, v113
	v_lshlrev_b32_e32 v178, 11, v6
	s_waitcnt lgkmcnt(6)
	v_cvt_pk_bf16_f32 v2, v8, v10
	s_waitcnt lgkmcnt(4)
	v_cvt_pk_bf16_f32 v3, v12, v14
	s_waitcnt lgkmcnt(2)
	v_cvt_pk_bf16_f32 v4, v16, v18
	s_waitcnt lgkmcnt(0)
	v_cvt_pk_bf16_f32 v5, v20, v24
	v_lshl_add_u64 v[6:7], v[22:23], 0, v[178:179]
	global_store_dwordx4 v[6:7], v[2:5], off nt
	v_or_b32_e32 v6, s4, v115
	v_lshlrev_b32_e32 v178, 11, v6
	v_cvt_pk_bf16_f32 v2, v9, v11
	v_cvt_pk_bf16_f32 v3, v13, v15
	v_cvt_pk_bf16_f32 v4, v17, v19
	v_cvt_pk_bf16_f32 v5, v21, v25
	v_lshl_add_u64 v[6:7], v[22:23], 0, v[178:179]
	global_store_dwordx4 v[6:7], v[2:5], off nt
	s_waitcnt lgkmcnt(0)

; #define LAS __attribute__((address_space(3)))
; __device__ __forceinline__ unsigned pk2(float lo, float hi) { const f32x2_g v = {lo, hi}; return __builtin_bit_cast(unsigned, __builtin_convertvector(v, bf16x2_g)); }
; template <class RowMap>
; __device__ __forceinline__ void transpose_item(const float* W, int K, int N, int ldw, bf16_t* WT, const RowMap& rm, LAS float* scr, int item, int lane, const float* kscale = nullptr) {
;     const int nblk = N / 64, kb = item / nblk, nb = item % nblk, k0 = 64 * kb, n0 = 64 * nb;
;     f32x4 v[16]; float ksc[16];
; #pragma unroll
;     for (int i = 0; i < 16; ++i) { const int kk = 4 * i + (lane >> 4), c4 = (lane & 15) * 4;
;         v[i] = __builtin_nontemporal_load((const f32x4*)(W + (size_t)(k0 + kk) * ldw + n0 + c4)); ksc[i] = kscale ? kscale[k0 + kk] : 1.0f; }
;     __builtin_amdgcn_sched_barrier(0);
; #pragma unroll
;     for (int i = 0; i < 16; ++i) { const int kk = 4 * i + (lane >> 4), c4 = (lane & 15) * 4; const f32x4 w = kscale ? v[i] * ksc[i] : v[i];
;         scr[kk * 65 + c4] = w[0]; scr[kk * 65 + c4 + 1] = w[1]; scr[kk * 65 + c4 + 2] = w[2]; scr[kk * 65 + c4 + 3] = w[3]; }
;     asm volatile("s_waitcnt lgkmcnt(0)" ::: "memory");
;     const int c = lane & 7;
; #pragma unroll
;     for (int j = 0; j < 8; ++j) { const int n = (lane >> 3) + 8 * j; const LAS float* s = scr + (8 * c) * 65 + n;
;         u32x4 o; o.x = pk2(s[0 * 65], s[1 * 65]); o.y = pk2(s[2 * 65], s[3 * 65]); o.z = pk2(s[4 * 65], s[5 * 65]); o.w = pk2(s[6 * 65], s[7 * 65]);
;         __builtin_nontemporal_store(o, (u32x4*)(WT + (size_t)rm(n0 + n) * K + k0 + 8 * c)); }
.LBB0_98:
	s_andn2_b64 vcc, exec, s[4:5]
	s_cbranch_vccnz .LBB0_11
	s_mul_hi_i32 s4, s0, 0x15390949
	s_lshr_b32 s5, s4, 31
	s_ashr_i32 s4, s4, 4
	s_add_i32 s7, s4, s5
	s_mul_i32 s4, s7, 0xffffcfc0
	s_add_i32 s4, s26, s4
	s_lshl_b32 s6, s7, 6
	s_ashr_i32 s5, s4, 31
	v_or_b32_e32 v62, s6, v67
	v_lshl_add_u64 v[58:59], s[4:5], 2, v[92:93]
	v_mad_i64_i32 v[2:3], s[20:21], v62, s15, v[58:59]
	v_or_b32_e32 v4, 4, v62
	v_or_b32_e32 v10, 8, v62
	v_or_b32_e32 v12, 12, v62
	v_or_b32_e32 v18, 16, v62
	v_or_b32_e32 v20, 20, v62
	v_or_b32_e32 v26, 24, v62
	v_or_b32_e32 v28, 28, v62
	v_or_b32_e32 v34, 32, v62
	v_or_b32_e32 v36, 36, v62
	v_or_b32_e32 v42, 40, v62
	v_or_b32_e32 v44, 44, v62
	v_or_b32_e32 v50, 48, v62
	v_or_b32_e32 v52, 52, v62
	v_or_b32_e32 v60, 56, v62
	v_or_b32_e32 v62, 60, v62
	v_mad_i64_i32 v[6:7], s[20:21], v4, s15, v[58:59]
	v_mad_i64_i32 v[10:11], s[20:21], v10, s15, v[58:59]
	v_mad_i64_i32 v[14:15], s[20:21], v12, s15, v[58:59]
	v_mad_i64_i32 v[18:19], s[20:21], v18, s15, v[58:59]
	v_mad_i64_i32 v[22:23], s[20:21], v20, s15, v[58:59]
	v_mad_i64_i32 v[26:27], s[20:21], v26, s15, v[58:59]
	v_mad_i64_i32 v[30:31], s[20:21], v28, s15, v[58:59]
	v_mad_i64_i32 v[34:35], s[20:21], v34, s15, v[58:59]
	v_mad_i64_i32 v[38:39], s[20:21], v36, s15, v[58:59]
	v_mad_i64_i32 v[42:43], s[20:21], v42, s15, v[58:59]
	v_mad_i64_i32 v[46:47], s[20:21], v44, s15, v[58:59]
	v_mad_i64_i32 v[50:51], s[20:21], v50, s15, v[58:59]
	v_mad_i64_i32 v[54:55], s[20:21], v52, s15, v[58:59]
	v_mad_i64_i32 v[60:61], s[20:21], v60, s15, v[58:59]
	v_mad_i64_i32 v[62:63], s[20:21], v62, s15, v[58:59]
	global_load_dwordx4 v[2:5], v[2:3], off nt
	s_nop 0
	global_load_dwordx4 v[6:9], v[6:7], off nt
	s_nop 0
	global_load_dwordx4 v[10:13], v[10:11], off nt
	s_nop 0
	global_load_dwordx4 v[14:17], v[14:15], off nt
	s_nop 0
	global_load_dwordx4 v[18:21], v[18:19], off nt
	s_nop 0
	global_load_dwordx4 v[22:25], v[22:23], off nt
	s_nop 0
	global_load_dwordx4 v[26:29], v[26:27], off nt
	s_nop 0
	global_load_dwordx4 v[30:33], v[30:31], off nt
	s_nop 0
	global_load_dwordx4 v[34:37], v[34:35], off nt
	s_nop 0
	global_load_dwordx4 v[38:41], v[38:39], off nt
	s_nop 0
	global_load_dwordx4 v[42:45], v[42:43], off nt
	s_nop 0
	global_load_dwordx4 v[46:49], v[46:47], off nt
	s_nop 0
	global_load_dwordx4 v[50:53], v[50:51], off nt
	s_nop 0
	global_load_dwordx4 v[54:57], v[54:55], off nt
	s_nop 0
	global_load_dwordx4 v[58:61], v[60:61], off nt
	s_nop 0
	global_load_dwordx4 v[62:65], v[62:63], off nt
	s_mulk_i32 s7, 0xc1
	s_sub_i32 s5, s0, s7
	s_lshl_b32 s5, s5, 6
	s_waitcnt vmcnt(15)
	ds_write2_b32 v69, v2, v3 offset1:1
	ds_write2_b32 v69, v4, v5 offset0:2 offset1:3
	v_add_u32_e32 v2, 0x410, v69
	s_waitcnt vmcnt(14)
	ds_write2_b32 v2, v6, v7 offset1:1
	v_add_u32_e32 v2, 0x418, v69
	ds_write2_b32 v2, v8, v9 offset1:1
	v_add_u32_e32 v2, 0x820, v69
	s_waitcnt vmcnt(13)
	ds_write2_b32 v2, v10, v11 offset1:1
	v_add_u32_e32 v2, 0x828, v69
	ds_write2_b32 v2, v12, v13 offset1:1
	v_add_u32_e32 v2, 0xc30, v69
	s_waitcnt vmcnt(12)
	ds_write2_b32 v2, v14, v15 offset1:1
	v_add_u32_e32 v2, 0xc38, v69
	ds_write2_b32 v2, v16, v17 offset1:1
	v_add_u32_e32 v2, 0x1040, v69
	s_waitcnt vmcnt(11)
	ds_write2_b32 v2, v18, v19 offset1:1
	v_add_u32_e32 v2, 0x1048, v69
	ds_write2_b32 v2, v20, v21 offset1:1
	v_add_u32_e32 v2, 0x1450, v69
	s_waitcnt vmcnt(10)
	ds_write2_b32 v2, v22, v23 offset1:1
	v_add_u32_e32 v2, 0x1458, v69
	ds_write2_b32 v2, v24, v25 offset1:1
	v_add_u32_e32 v2, 0x1860, v69
	s_waitcnt vmcnt(9)
	ds_write2_b32 v2, v26, v27 offset1:1
	v_add_u32_e32 v2, 0x1868, v69
	ds_write2_b32 v2, v28, v29 offset1:1
	v_add_u32_e32 v2, 0x1c70, v69
	s_waitcnt vmcnt(8)
	ds_write2_b32 v2, v30, v31 offset1:1
	v_add_u32_e32 v2, 0x1c78, v69
	ds_write2_b32 v2, v32, v33 offset1:1
	v_add_u32_e32 v2, 0x2080, v69
	s_waitcnt vmcnt(7)
	ds_write2_b32 v2, v34, v35 offset1:1
	v_add_u32_e32 v2, 0x2088, v69
	ds_write2_b32 v2, v36, v37 offset1:1
	v_add_u32_e32 v2, 0x2490, v69
	s_waitcnt vmcnt(6)
	ds_write2_b32 v2, v38, v39 offset1:1
	v_add_u32_e32 v2, 0x2498, v69
	ds_write2_b32 v2, v40, v41 offset1:1
	v_add_u32_e32 v2, 0x28a0, v69
	s_waitcnt vmcnt(5)
	ds_write2_b32 v2, v42, v43 offset1:1
	v_add_u32_e32 v2, 0x28a8, v69
	ds_write2_b32 v2, v44, v45 offset1:1
	v_add_u32_e32 v2, 0x2cb0, v69
	s_waitcnt vmcnt(4)
	ds_write2_b32 v2, v46, v47 offset1:1
	v_add_u32_e32 v2, 0x2cb8, v69
	ds_write2_b32 v2, v48, v49 offset1:1
	v_add_u32_e32 v2, 0x30c0, v69
	s_waitcnt vmcnt(3)
	ds_write2_b32 v2, v50, v51 offset1:1
	v_add_u32_e32 v2, 0x30c8, v69
	ds_write2_b32 v2, v52, v53 offset1:1
	v_add_u32_e32 v2, 0x34d0, v69
	s_waitcnt vmcnt(2)
	ds_write2_b32 v2, v54, v55 offset1:1
	v_add_u32_e32 v2, 0x34d8, v69
	ds_write2_b32 v2, v56, v57 offset1:1
	v_add_u32_e32 v2, 0x38e0, v69
	s_waitcnt vmcnt(1)
	ds_write2_b32 v2, v58, v59 offset1:1
	v_add_u32_e32 v2, 0x38e8, v69
	ds_write2_b32 v2, v60, v61 offset1:1
	v_add_u32_e32 v2, 0x3cf0, v69
	s_waitcnt vmcnt(0)
	ds_write2_b32 v2, v62, v63 offset1:1
	v_add_u32_e32 v2, 0x3cf8, v69
	ds_write2_b32 v2, v64, v65 offset1:1
	s_waitcnt lgkmcnt(0)
	v_add_u32_e32 v15, 0x400, v101
	ds_read2_b32 v[4:5], v101 offset1:65
	ds_read2_b32 v[6:7], v101 offset0:130 offset1:195
	ds_read2_b32 v[8:9], v15 offset0:4 offset1:69
	ds_read2_b32 v[10:11], v15 offset0:134 offset1:199
	v_add_u32_e32 v14, s4, v71
	s_movk_i32 s7, 0x3ff
	v_or_b32_e32 v12, s5, v71
	v_cmp_lt_i32_e32 vcc, s7, v14
	s_and_saveexec_b64 s[20:21], vcc
	s_cbranch_execz .LBB0_113
	s_cmpk_gt_u32 s4, 0x43f
	s_mov_b64 s[22:23], -1
	s_cbranch_scc0 .LBB0_110
	s_cmpk_gt_u32 s4, 0xc3f
	s_cbranch_scc0 .LBB0_107
	s_cmpk_gt_u32 s4, 0x143f
	s_cbranch_scc0 .LBB0_104
	v_subrev_u32_e32 v2, 64, v12
	s_mov_b64 s[22:23], 0
